# T15 loop with V stream delayed one tile: V back to 2 statically addressed LDS buffers, no per-stage address VALU, no rotation state
# speedup vs baseline: 1.0191x; 1.0040x over previous
; #define MFMA32(a, b, c) __builtin_amdgcn_mfma_f32_32x32x16_bf16((a), (b), (c), 0, 0, 0)
; #define AT_LOAD(SET, IT) { const int kl_ = AT_KB(IT); \
;     _Pragma("unroll") for (int i = 0; i < KPT; ++i) kreg[SET][i] = *(const u32x4*)(Kg + (size_t)kl_ * DQK + (tid + 256 * i) * 8); \
;     _Pragma("unroll") for (int i = 0; i < 2; ++i) vreg[SET][i] = *(const u32x4*)(Vg + (size_t)kl_ * 64 + (tid + 256 * i) * 8); \
;     __builtin_amdgcn_sched_barrier(0); }
; #define AT_WRITE(SET, BUFI) { \
;     _Pragma("unroll") for (int i = 0; i < KPT; ++i) { const int c = tid + 256 * i, row = c / KCH, kcol = c % KCH; *(u32x4*)(Ks + (BUFI) * KBUF + row * KSTR + kcol * 8) = kreg[SET][i]; } \
;     _Pragma("unroll") for (int i = 0; i < 2; ++i) { const int c = tid + 256 * i; *(u32x4*)(Vs + (BUFI) * VBUF + (c >> 3) * VSTR + (c & 7) * 8) = vreg[SET][i]; } }
; template <int DQK, bool SB, bool SMAX>
; DI void attn_item(const Params& p, char* smem, int bh, int qb, float Mb) {
;     ...
;   const int blk = (lane >> 4) & 1, tq = (lane & 15) >> 2, tp = lane & 3;
;   const int voff = (4 * h + tq) * VSTR + 16 * blk + 4 * tp;
;   AT_LOAD(0, 0)
;   AT_WRITE(0, 0)
;   AT_LOAD(0, 1)
;   __syncthreads();
;   bool stop = false;
;   for (int it2 = 0; it2 < nt && !stop; it2 += 2) {
; #pragma unroll
;    for (int st2 = 0; st2 < 2; ++st2) {
;     const int it = it2 + st2;
;     const int kb0 = AT_KB(it);
;     const bf16_t* kc = Ks + st2 * KBUF;
;     const bf16_t* vc = Vs + st2 * VBUF;
;     const bool active = kb0 < qw0 + 32;
;     f32x16 st[2];
;     if (active) {
; #pragma unroll
;       for (int kb = 0; kb < 2; ++kb)
; #pragma unroll
;         for (int i = 0; i < 16; ++i) st[kb][i] = SMAX ? negM[i] : 0.f;
; #pragma unroll
;       for (int ks = 0; ks < NKS; ++ks)
; #pragma unroll
;         for (int kb = 0; kb < 2; ++kb) {
;           const bf16x8 a = *(const bf16x8*)(kc + (kb * 32 + r) * KSTR + ks * 16 + h * 8);
;           st[kb] = MFMA32(a, qf[ks], st[kb]);
;         }
;     }
;     __builtin_amdgcn_sched_barrier(0);
;     AT_WRITE(0, st2 ^ 1)
;     AT_LOAD(0, (it + 2 < nt) ? it + 2 : nt - 1)
.LBB0_470:
	s_and_b64 vcc, exec, s[2:3]
	s_cbranch_vccz .LBB0_425
	global_load_dwordx4 v[132:135], v[186:187], off
	global_load_dwordx4 v[136:139], v[188:189], off
	global_load_dwordx4 v[140:143], v[190:191], off
	global_load_dwordx4 v[144:147], v[192:193], off
	global_load_dwordx4 v[148:151], v[194:195], off
	s_waitcnt vmcnt(9)
	ds_write_b128 v206, v[112:115]
	s_waitcnt vmcnt(8)
	ds_write_b128 v207, v[116:119]
	s_waitcnt vmcnt(7)
	ds_write_b128 v208, v[120:123]
	s_waitcnt vmcnt(6)
	ds_write_b128 v203, v[124:127] offset:26624
	s_waitcnt vmcnt(5)
	ds_write_b128 v204, v[128:131] offset:26624
	s_and_b64 vcc, exec, s[12:13]
	s_waitcnt lgkmcnt(0)
	s_barrier
	s_cbranch_vccnz .LBB0_423
	v_mov_b32_e32 v16, v177
	v_mov_b32_e32 v17, v177
	v_mov_b32_e32 v18, v177
	v_mov_b32_e32 v19, v177
	v_mov_b32_e32 v20, v177
	v_mov_b32_e32 v21, v177
	v_mov_b32_e32 v22, v177
	v_mov_b32_e32 v23, v177
	v_mov_b32_e32 v24, v177
	v_mov_b32_e32 v25, v177
	v_mov_b32_e32 v26, v177
	v_mov_b32_e32 v27, v177
	v_mov_b32_e32 v28, v177
	v_mov_b32_e32 v29, v177
	v_mov_b32_e32 v30, v177
	v_mov_b32_e32 v31, v177
	v_mov_b32_e32 v32, v177
	v_mov_b32_e32 v33, v177
	v_mov_b32_e32 v34, v177
	v_mov_b32_e32 v35, v177
	v_mov_b32_e32 v36, v177
	v_mov_b32_e32 v37, v177
	v_mov_b32_e32 v38, v177
	v_mov_b32_e32 v39, v177
	v_mov_b32_e32 v40, v177
	v_mov_b32_e32 v41, v177
	v_mov_b32_e32 v42, v177
	v_mov_b32_e32 v43, v177
	v_mov_b32_e32 v44, v177
	v_mov_b32_e32 v45, v177
	v_mov_b32_e32 v46, v177
	v_mov_b32_e32 v47, v177
	v_mov_b32_e32 v152, 0
	v_add_u32_e32 v153, v178, v202
	v_add_u32_e32 v154, v198, v200
	v_readfirstlane_b32 s20, v211
	s_add_i32 s4, s1, -1
	s_lshr_b32 s21, s16, 1
	s_mov_b32 s14, 2
	s_mul_i32 s3, s0, 0x180000
	s_add_u32 s22, s82, s3
	s_addc_u32 s23, s83, 0
	s_add_u32 s22, s22, 0x1000
	s_addc_u32 s23, s23, 0
	s_lshl_b32 s3, s0, 20
	s_add_u32 s38, s84, s3
	s_addc_u32 s39, s85, 0
	s_add_u32 s38, s38, 0x1000
	s_addc_u32 s39, s39, 0
	ds_read_b128 v[216:219], v153
	ds_read_b128 v[220:223], v153 offset:6656
	ds_read_b128 v[228:231], v153 offset:32
	s_min_i32 s2, s14, s4
	s_mul_i32 s3, s2, 0x3000
	s_add_u32 s30, s22, s3
	s_addc_u32 s31, s23, 0
	s_add_u32 s34, s30, 0x1000
	s_addc_u32 s35, s31, 0
	s_add_i32 s3, s14, -1
	s_min_i32 s3, s3, s4
	s_lshl_b32 s3, s3, 13
	s_add_u32 s36, s38, s3
	s_addc_u32 s37, s39, 0
	global_load_dwordx4 v[112:115], v174, s[30:31] offset:-4096
	global_load_dwordx4 v[116:119], v174, s[30:31]
	global_load_dwordx4 v[120:123], v174, s[34:35]
	global_load_dwordx4 v[124:127], v174, s[36:37] offset:-4096
	global_load_dwordx4 v[128:131], v174, s[36:37]
	s_waitcnt vmcnt(9)
	ds_write_b128 v206, v[132:135] offset:13312
	s_waitcnt vmcnt(8)
	ds_write_b128 v207, v[136:139] offset:13312
	s_waitcnt vmcnt(7)
	ds_write_b128 v208, v[140:143] offset:13312
	s_waitcnt vmcnt(6)
	ds_write_b128 v203, v[144:147] offset:35840
	s_waitcnt vmcnt(5)
	ds_write_b128 v203, v[148:151] offset:40448
	s_waitcnt lgkmcnt(7)
	v_mfma_f32_32x32x16_bf16 v[48:63], v[216:219], v[80:83], 0
	ds_read_b128 v[216:219], v153 offset:6688
	s_waitcnt lgkmcnt(7)
	v_mfma_f32_32x32x16_bf16 v[64:79], v[220:223], v[80:83], 0
	ds_read_b128 v[220:223], v153 offset:64
	s_waitcnt lgkmcnt(7)
	v_mfma_f32_32x32x16_bf16 v[48:63], v[228:231], v[84:87], v[48:63]
	ds_read_b128 v[228:231], v153 offset:6720
	s_waitcnt lgkmcnt(2)
	v_mfma_f32_32x32x16_bf16 v[64:79], v[216:219], v[84:87], v[64:79]
	ds_read_b128 v[216:219], v153 offset:96
	s_waitcnt lgkmcnt(2)
	v_mfma_f32_32x32x16_bf16 v[48:63], v[220:223], v[88:91], v[48:63]
	ds_read_b128 v[220:223], v153 offset:6752
	s_waitcnt lgkmcnt(2)
	v_mfma_f32_32x32x16_bf16 v[64:79], v[228:231], v[88:91], v[64:79]
	ds_read_b128 v[228:231], v153 offset:128
	s_waitcnt lgkmcnt(2)
	v_mfma_f32_32x32x16_bf16 v[48:63], v[216:219], v[92:95], v[48:63]
	ds_read_b128 v[216:219], v153 offset:6784
	s_waitcnt lgkmcnt(2)
	v_mfma_f32_32x32x16_bf16 v[64:79], v[220:223], v[92:95], v[64:79]
	ds_read_b128 v[220:223], v153 offset:160
	s_waitcnt lgkmcnt(2)
	v_mfma_f32_32x32x16_bf16 v[48:63], v[228:231], v[104:107], v[48:63]
	ds_read_b128 v[228:231], v153 offset:6816
	s_waitcnt lgkmcnt(2)
	v_mfma_f32_32x32x16_bf16 v[64:79], v[216:219], v[104:107], v[64:79]
	s_waitcnt lgkmcnt(1)
	v_mfma_f32_32x32x16_bf16 v[48:63], v[220:223], v[108:111], v[48:63]
	s_waitcnt lgkmcnt(0)
	v_mfma_f32_32x32x16_bf16 v[64:79], v[228:231], v[108:111], v[64:79]
	s_waitcnt lgkmcnt(0)
	s_barrier
	s_add_i32 s14, s14, 1
	s_cmp_eq_u32 s21, 0
	s_cbranch_scc1 .Lt15_tail
; #define MFMA32(a, b, c) __builtin_amdgcn_mfma_f32_32x32x16_bf16((a), (b), (c), 0, 0, 0)
; template <int DQK, bool SB, bool SMAX>
; DI void attn_item(const Params& p, char* smem, int bh, int qb, float Mb) {
;     ...
; #pragma unroll
;       for (int kk = 0; kk < 4; ++kk)
; #pragma unroll
;         for (int db = 0; db < 2; ++db) {
;           const s16x4 v0 = __builtin_amdgcn_ds_read_tr16_b64_v4i16((lds_s16x4*)(vc + voff + (16 * kk) * VSTR + 32 * db));
;           const s16x4 v1 = __builtin_amdgcn_ds_read_tr16_b64_v4i16((lds_s16x4*)(vc + voff + (16 * kk + 8) * VSTR + 32 * db));
;           const bf16x8 vf = __builtin_shufflevector(v0, v1, 0, 1, 2, 3, 4, 5, 6, 7);
;           O[db] = MFMA32(vf, pk[kk], O[db]);
;         }
.Lt15_loop:
	ds_read_b128 v[216:219], v153 offset:13312
	ds_read_b128 v[220:223], v153 offset:19968
	ds_read_b128 v[228:231], v153 offset:13344
	ds_read_b64_tr_b16 v[236:237], v154 offset:26624
	ds_read_b64_tr_b16 v[238:239], v154 offset:27776
	ds_read_b64_tr_b16 v[244:245], v154 offset:26688
	ds_read_b64_tr_b16 v[246:247], v154 offset:27840
	ds_read_b64_tr_b16 v[248:249], v154 offset:28928
	ds_read_b64_tr_b16 v[250:251], v154 offset:30080
	s_min_i32 s2, s14, s4
	s_mul_i32 s3, s2, 0x3000
	s_add_u32 s30, s22, s3
	s_addc_u32 s31, s23, 0
	s_add_u32 s34, s30, 0x1000
	s_addc_u32 s35, s31, 0
	s_add_i32 s3, s14, -1
	s_min_i32 s3, s3, s4
	s_lshl_b32 s3, s3, 13
	s_add_u32 s36, s38, s3
	s_addc_u32 s37, s39, 0
	global_load_dwordx4 v[132:135], v174, s[30:31] offset:-4096
	global_load_dwordx4 v[136:139], v174, s[30:31]
	global_load_dwordx4 v[140:143], v174, s[34:35]
	global_load_dwordx4 v[144:147], v174, s[36:37] offset:-4096
	global_load_dwordx4 v[148:151], v174, s[36:37]
	s_waitcnt vmcnt(9)
	ds_write_b128 v206, v[112:115]
	s_waitcnt vmcnt(8)
	ds_write_b128 v207, v[116:119]
	s_waitcnt vmcnt(7)
	ds_write_b128 v208, v[120:123]
	s_waitcnt vmcnt(6)
	ds_write_b128 v203, v[124:127] offset:35840
	s_waitcnt vmcnt(5)
	ds_write_b128 v203, v[128:131] offset:40448
	v_exp_f32_e32 v48, v48
	v_exp_f32_e32 v49, v49
	v_exp_f32_e32 v50, v50
	v_exp_f32_e32 v51, v51
	s_waitcnt lgkmcnt(13)
	v_mfma_f32_32x32x16_bf16 v[0:15], v[216:219], v[80:83], 0
	ds_read_b128 v[216:219], v153 offset:20000
	v_exp_f32_e32 v52, v52
	v_add_f32_e32 v224, v49, v48
	v_cvt_pk_bf16_f32 v188, v48, v49
	v_exp_f32_e32 v53, v53
	s_waitcnt lgkmcnt(13)
	v_mfma_f32_32x32x16_bf16 v[156:171], v[220:223], v[80:83], 0
	ds_read_b128 v[220:223], v153 offset:13376
	v_add_f32_e32 v224, v50, v224
	v_exp_f32_e32 v54, v54
	v_add_f32_e32 v224, v51, v224
	v_cvt_pk_bf16_f32 v189, v50, v51
	s_waitcnt lgkmcnt(13)
	v_mfma_f32_32x32x16_bf16 v[0:15], v[228:231], v[84:87], v[0:15]
	ds_read_b128 v[228:231], v153 offset:20032
	v_exp_f32_e32 v55, v55
	v_add_f32_e32 v224, v52, v224
	v_exp_f32_e32 v56, v56
	v_add_f32_e32 v224, v53, v224
	s_waitcnt lgkmcnt(2)
	v_mfma_f32_32x32x16_bf16 v[156:171], v[216:219], v[84:87], v[156:171]
	ds_read_b128 v[216:219], v153 offset:13408
	v_cvt_pk_bf16_f32 v190, v52, v53
	v_exp_f32_e32 v57, v57
	v_add_f32_e32 v224, v54, v224
	v_exp_f32_e32 v58, v58
	s_waitcnt lgkmcnt(2)
	v_mfma_f32_32x32x16_bf16 v[0:15], v[220:223], v[88:91], v[0:15]
	ds_read_b128 v[220:223], v153 offset:20064
	v_add_f32_e32 v224, v55, v224
	v_cvt_pk_bf16_f32 v191, v54, v55
	v_exp_f32_e32 v59, v59
	v_add_f32_e32 v224, v56, v224
	s_nop 0
	v_mfma_f32_32x32x16_bf16 v[32:47], v[236:239], v[188:191], v[32:47]
	ds_read_b64_tr_b16 v[236:237], v154 offset:28992
	ds_read_b64_tr_b16 v[238:239], v154 offset:30144
	v_exp_f32_e32 v60, v60
	v_add_f32_e32 v224, v57, v224
	v_cvt_pk_bf16_f32 v192, v56, v57
	v_exp_f32_e32 v61, v61
	v_mfma_f32_32x32x16_bf16 v[16:31], v[244:247], v[188:191], v[16:31]
	ds_read_b64_tr_b16 v[244:245], v154 offset:31232
	ds_read_b64_tr_b16 v[246:247], v154 offset:32384
	v_add_f32_e32 v224, v58, v224
	v_exp_f32_e32 v62, v62
	v_add_f32_e32 v224, v59, v224
	v_cvt_pk_bf16_f32 v193, v58, v59
	s_waitcnt lgkmcnt(6)
	v_mfma_f32_32x32x16_bf16 v[156:171], v[228:231], v[88:91], v[156:171]
	ds_read_b128 v[228:231], v153 offset:13440
	v_exp_f32_e32 v63, v63
	v_add_f32_e32 v224, v60, v224
	v_add_f32_e32 v224, v61, v224
	v_add_f32_e32 v224, v62, v224
	s_waitcnt lgkmcnt(6)
	v_mfma_f32_32x32x16_bf16 v[0:15], v[216:219], v[92:95], v[0:15]
	ds_read_b128 v[216:219], v153 offset:20096
	v_add_f32_e32 v224, v63, v224
	v_cvt_pk_bf16_f32 v194, v60, v61
	v_cvt_pk_bf16_f32 v195, v62, v63
	v_exp_f32_e32 v64, v64
	s_waitcnt lgkmcnt(6)
	v_mfma_f32_32x32x16_bf16 v[156:171], v[220:223], v[92:95], v[156:171]
	ds_read_b128 v[220:223], v153 offset:13472
	v_exp_f32_e32 v65, v65
	v_exp_f32_e32 v66, v66
	v_exp_f32_e32 v67, v67
	v_add_f32_e32 v224, v64, v224
	v_mfma_f32_32x32x16_bf16 v[32:47], v[248:251], v[192:195], v[32:47]
	ds_read_b64_tr_b16 v[248:249], v154 offset:31296
	ds_read_b64_tr_b16 v[250:251], v154 offset:32448
	v_exp_f32_e32 v68, v68
	v_add_f32_e32 v224, v65, v224
	v_cvt_pk_bf16_f32 v188, v64, v65
	v_exp_f32_e32 v69, v69
	s_waitcnt lgkmcnt(7)
	v_mfma_f32_32x32x16_bf16 v[16:31], v[236:239], v[192:195], v[16:31]
	ds_read_b64_tr_b16 v[236:237], v154 offset:33536
	ds_read_b64_tr_b16 v[238:239], v154 offset:34688
	v_add_f32_e32 v224, v66, v224
	v_exp_f32_e32 v70, v70
	v_add_f32_e32 v224, v67, v224
	v_cvt_pk_bf16_f32 v189, v66, v67
	s_waitcnt lgkmcnt(6)
	v_mfma_f32_32x32x16_bf16 v[0:15], v[228:231], v[104:107], v[0:15]
	ds_read_b128 v[228:231], v153 offset:20128
	v_exp_f32_e32 v71, v71
	v_add_f32_e32 v224, v68, v224
	v_exp_f32_e32 v72, v72
	v_add_f32_e32 v224, v69, v224
	s_waitcnt lgkmcnt(6)
	v_mfma_f32_32x32x16_bf16 v[156:171], v[216:219], v[104:107], v[156:171]
	v_cvt_pk_bf16_f32 v190, v68, v69
	v_exp_f32_e32 v73, v73
	v_add_f32_e32 v224, v70, v224
	v_exp_f32_e32 v74, v74
	s_waitcnt lgkmcnt(5)
	v_mfma_f32_32x32x16_bf16 v[0:15], v[220:223], v[108:111], v[0:15]
	v_add_f32_e32 v224, v71, v224
	v_cvt_pk_bf16_f32 v191, v70, v71
	v_exp_f32_e32 v75, v75
	v_add_f32_e32 v224, v72, v224
	s_nop 0
	v_mfma_f32_32x32x16_bf16 v[32:47], v[244:247], v[188:191], v[32:47]
	ds_read_b64_tr_b16 v[244:245], v154 offset:33600
	ds_read_b64_tr_b16 v[246:247], v154 offset:34752
	v_exp_f32_e32 v76, v76
	v_add_f32_e32 v224, v73, v224
	v_cvt_pk_bf16_f32 v192, v72, v73
	v_exp_f32_e32 v77, v77
	s_waitcnt lgkmcnt(5)
	v_mfma_f32_32x32x16_bf16 v[16:31], v[248:251], v[188:191], v[16:31]
	v_add_f32_e32 v224, v74, v224
	v_exp_f32_e32 v78, v78
	v_add_f32_e32 v224, v75, v224
	v_cvt_pk_bf16_f32 v193, v74, v75
	s_waitcnt lgkmcnt(2)
	v_mfma_f32_32x32x16_bf16 v[156:171], v[228:231], v[108:111], v[156:171]
	v_exp_f32_e32 v79, v79
	v_add_f32_e32 v224, v76, v224
	v_add_f32_e32 v224, v77, v224
	v_add_f32_e32 v224, v78, v224
	v_add_f32_e32 v224, v79, v224
	v_cvt_pk_bf16_f32 v194, v76, v77
	v_cvt_pk_bf16_f32 v195, v78, v79
	s_nop 1
	v_mfma_f32_32x32x16_bf16 v[32:47], v[236:239], v[192:195], v[32:47]
	s_waitcnt lgkmcnt(0)
	v_mfma_f32_32x32x16_bf16 v[16:31], v[244:247], v[192:195], v[16:31]
	v_add_f32_e32 v152, v152, v224
	s_waitcnt lgkmcnt(0)
	s_barrier
; #define MFMA32(a, b, c) __builtin_amdgcn_mfma_f32_32x32x16_bf16((a), (b), (c), 0, 0, 0)
; template <int DQK, bool SB, bool SMAX>
; DI void attn_item(const Params& p, char* smem, int bh, int qb, float Mb) {
;     ...
; #pragma unroll
;       for (int kk = 0; kk < 4; ++kk)
; #pragma unroll
;         for (int db = 0; db < 2; ++db) {
;           const s16x4 v0 = __builtin_amdgcn_ds_read_tr16_b64_v4i16((lds_s16x4*)(vc + voff + (16 * kk) * VSTR + 32 * db));
;           const s16x4 v1 = __builtin_amdgcn_ds_read_tr16_b64_v4i16((lds_s16x4*)(vc + voff + (16 * kk + 8) * VSTR + 32 * db));
;           const bf16x8 vf = __builtin_shufflevector(v0, v1, 0, 1, 2, 3, 4, 5, 6, 7);
;           O[db] = MFMA32(vf, pk[kk], O[db]);
;         }
	s_add_i32 s14, s14, 1
	ds_read_b128 v[216:219], v153
	ds_read_b128 v[220:223], v153 offset:6656
	ds_read_b128 v[228:231], v153 offset:32
	ds_read_b64_tr_b16 v[236:237], v154 offset:35840
	ds_read_b64_tr_b16 v[238:239], v154 offset:36992
	ds_read_b64_tr_b16 v[244:245], v154 offset:35904
	ds_read_b64_tr_b16 v[246:247], v154 offset:37056
	ds_read_b64_tr_b16 v[248:249], v154 offset:38144
	ds_read_b64_tr_b16 v[250:251], v154 offset:39296
	s_min_i32 s2, s14, s4
	s_mul_i32 s3, s2, 0x3000
	s_add_u32 s30, s22, s3
	s_addc_u32 s31, s23, 0
	s_add_u32 s34, s30, 0x1000
	s_addc_u32 s35, s31, 0
	s_add_i32 s3, s14, -1
	s_min_i32 s3, s3, s4
	s_lshl_b32 s3, s3, 13
	s_add_u32 s36, s38, s3
	s_addc_u32 s37, s39, 0
	global_load_dwordx4 v[112:115], v174, s[30:31] offset:-4096
	global_load_dwordx4 v[116:119], v174, s[30:31]
	global_load_dwordx4 v[120:123], v174, s[34:35]
	global_load_dwordx4 v[124:127], v174, s[36:37] offset:-4096
	global_load_dwordx4 v[128:131], v174, s[36:37]
	s_waitcnt vmcnt(9)
	ds_write_b128 v206, v[132:135] offset:13312
	s_waitcnt vmcnt(8)
	ds_write_b128 v207, v[136:139] offset:13312
	s_waitcnt vmcnt(7)
	ds_write_b128 v208, v[140:143] offset:13312
	s_waitcnt vmcnt(6)
	ds_write_b128 v203, v[144:147] offset:26624
	s_waitcnt vmcnt(5)
	ds_write_b128 v203, v[148:151] offset:31232
	v_exp_f32_e32 v0, v0
	v_exp_f32_e32 v1, v1
	v_exp_f32_e32 v2, v2
	v_exp_f32_e32 v3, v3
	s_waitcnt lgkmcnt(13)
	v_mfma_f32_32x32x16_bf16 v[48:63], v[216:219], v[80:83], 0
	ds_read_b128 v[216:219], v153 offset:6688
	v_exp_f32_e32 v4, v4
	v_add_f32_e32 v224, v1, v0
	v_cvt_pk_bf16_f32 v188, v0, v1
	v_exp_f32_e32 v5, v5
	s_waitcnt lgkmcnt(13)
	v_mfma_f32_32x32x16_bf16 v[64:79], v[220:223], v[80:83], 0
	ds_read_b128 v[220:223], v153 offset:64
	v_add_f32_e32 v224, v2, v224
	v_exp_f32_e32 v6, v6
	v_add_f32_e32 v224, v3, v224
	v_cvt_pk_bf16_f32 v189, v2, v3
	s_waitcnt lgkmcnt(13)
	v_mfma_f32_32x32x16_bf16 v[48:63], v[228:231], v[84:87], v[48:63]
	ds_read_b128 v[228:231], v153 offset:6720
	v_exp_f32_e32 v7, v7
	v_add_f32_e32 v224, v4, v224
	v_exp_f32_e32 v8, v8
	v_add_f32_e32 v224, v5, v224
	s_waitcnt lgkmcnt(2)
	v_mfma_f32_32x32x16_bf16 v[64:79], v[216:219], v[84:87], v[64:79]
	ds_read_b128 v[216:219], v153 offset:96
	v_cvt_pk_bf16_f32 v190, v4, v5
	v_exp_f32_e32 v9, v9
	v_add_f32_e32 v224, v6, v224
	v_exp_f32_e32 v10, v10
	s_waitcnt lgkmcnt(2)
	v_mfma_f32_32x32x16_bf16 v[48:63], v[220:223], v[88:91], v[48:63]
	ds_read_b128 v[220:223], v153 offset:6752
	v_add_f32_e32 v224, v7, v224
	v_cvt_pk_bf16_f32 v191, v6, v7
	v_exp_f32_e32 v11, v11
	v_add_f32_e32 v224, v8, v224
	s_nop 0
	v_mfma_f32_32x32x16_bf16 v[32:47], v[236:239], v[188:191], v[32:47]
	ds_read_b64_tr_b16 v[236:237], v154 offset:38208
	ds_read_b64_tr_b16 v[238:239], v154 offset:39360
	v_exp_f32_e32 v12, v12
	v_add_f32_e32 v224, v9, v224
	v_cvt_pk_bf16_f32 v192, v8, v9
	v_exp_f32_e32 v13, v13
	v_mfma_f32_32x32x16_bf16 v[16:31], v[244:247], v[188:191], v[16:31]
	ds_read_b64_tr_b16 v[244:245], v154 offset:40448
	ds_read_b64_tr_b16 v[246:247], v154 offset:41600
	v_add_f32_e32 v224, v10, v224
	v_exp_f32_e32 v14, v14
	v_add_f32_e32 v224, v11, v224
	v_cvt_pk_bf16_f32 v193, v10, v11
	s_waitcnt lgkmcnt(6)
	v_mfma_f32_32x32x16_bf16 v[64:79], v[228:231], v[88:91], v[64:79]
	ds_read_b128 v[228:231], v153 offset:128
	v_exp_f32_e32 v15, v15
	v_add_f32_e32 v224, v12, v224
	v_add_f32_e32 v224, v13, v224
	v_add_f32_e32 v224, v14, v224
	s_waitcnt lgkmcnt(6)
	v_mfma_f32_32x32x16_bf16 v[48:63], v[216:219], v[92:95], v[48:63]
	ds_read_b128 v[216:219], v153 offset:6784
	v_add_f32_e32 v224, v15, v224
	v_cvt_pk_bf16_f32 v194, v12, v13
	v_cvt_pk_bf16_f32 v195, v14, v15
	v_exp_f32_e32 v156, v156
	s_waitcnt lgkmcnt(6)
	v_mfma_f32_32x32x16_bf16 v[64:79], v[220:223], v[92:95], v[64:79]
	ds_read_b128 v[220:223], v153 offset:160
	v_exp_f32_e32 v157, v157
	v_exp_f32_e32 v158, v158
	v_exp_f32_e32 v159, v159
	v_add_f32_e32 v224, v156, v224
	v_mfma_f32_32x32x16_bf16 v[32:47], v[248:251], v[192:195], v[32:47]
	ds_read_b64_tr_b16 v[248:249], v154 offset:40512
	ds_read_b64_tr_b16 v[250:251], v154 offset:41664
	v_exp_f32_e32 v160, v160
	v_add_f32_e32 v224, v157, v224
	v_cvt_pk_bf16_f32 v188, v156, v157
	v_exp_f32_e32 v161, v161
	s_waitcnt lgkmcnt(7)
	v_mfma_f32_32x32x16_bf16 v[16:31], v[236:239], v[192:195], v[16:31]
	ds_read_b64_tr_b16 v[236:237], v154 offset:42752
	ds_read_b64_tr_b16 v[238:239], v154 offset:43904
	v_add_f32_e32 v224, v158, v224
	v_exp_f32_e32 v162, v162
	v_add_f32_e32 v224, v159, v224
	v_cvt_pk_bf16_f32 v189, v158, v159
	s_waitcnt lgkmcnt(6)
	v_mfma_f32_32x32x16_bf16 v[48:63], v[228:231], v[104:107], v[48:63]
	ds_read_b128 v[228:231], v153 offset:6816
	v_exp_f32_e32 v163, v163
	v_add_f32_e32 v224, v160, v224
	v_exp_f32_e32 v164, v164
	v_add_f32_e32 v224, v161, v224
	s_waitcnt lgkmcnt(6)
	v_mfma_f32_32x32x16_bf16 v[64:79], v[216:219], v[104:107], v[64:79]
	v_cvt_pk_bf16_f32 v190, v160, v161
	v_exp_f32_e32 v165, v165
	v_add_f32_e32 v224, v162, v224
	v_exp_f32_e32 v166, v166
	s_waitcnt lgkmcnt(5)
	v_mfma_f32_32x32x16_bf16 v[48:63], v[220:223], v[108:111], v[48:63]
	v_add_f32_e32 v224, v163, v224
	v_cvt_pk_bf16_f32 v191, v162, v163
	v_exp_f32_e32 v167, v167
	v_add_f32_e32 v224, v164, v224
	s_nop 0
	v_mfma_f32_32x32x16_bf16 v[32:47], v[244:247], v[188:191], v[32:47]
	ds_read_b64_tr_b16 v[244:245], v154 offset:42816
	ds_read_b64_tr_b16 v[246:247], v154 offset:43968
	v_exp_f32_e32 v168, v168
	v_add_f32_e32 v224, v165, v224
	v_cvt_pk_bf16_f32 v192, v164, v165
	v_exp_f32_e32 v169, v169
	s_waitcnt lgkmcnt(5)
	v_mfma_f32_32x32x16_bf16 v[16:31], v[248:251], v[188:191], v[16:31]
	v_add_f32_e32 v224, v166, v224
	v_exp_f32_e32 v170, v170
	v_add_f32_e32 v224, v167, v224
	v_cvt_pk_bf16_f32 v193, v166, v167
	s_waitcnt lgkmcnt(2)
	v_mfma_f32_32x32x16_bf16 v[64:79], v[228:231], v[108:111], v[64:79]
	v_exp_f32_e32 v171, v171
	v_add_f32_e32 v224, v168, v224
	v_add_f32_e32 v224, v169, v224
	v_add_f32_e32 v224, v170, v224
	v_add_f32_e32 v224, v171, v224
	v_cvt_pk_bf16_f32 v194, v168, v169
	v_cvt_pk_bf16_f32 v195, v170, v171
	s_nop 1
	v_mfma_f32_32x32x16_bf16 v[32:47], v[236:239], v[192:195], v[32:47]
	s_waitcnt lgkmcnt(0)
	v_mfma_f32_32x32x16_bf16 v[16:31], v[244:247], v[192:195], v[16:31]
	v_add_f32_e32 v152, v152, v224
	s_waitcnt lgkmcnt(0)
	s_barrier
	s_add_i32 s14, s14, 1
	s_add_i32 s21, s21, -1
	s_cmp_lg_u32 s21, 0
	s_cbranch_scc1 .Lt15_loop
; #define MFMA32(a, b, c) __builtin_amdgcn_mfma_f32_32x32x16_bf16((a), (b), (c), 0, 0, 0)
; DI int crow(int i, int h) { return (i & 3) + 8 * (i >> 2) + 4 * h; }
; #define AT_LOAD(SET, IT) { const int kl_ = AT_KB(IT); \
;     _Pragma("unroll") for (int i = 0; i < KPT; ++i) kreg[SET][i] = *(const u32x4*)(Kg + (size_t)kl_ * DQK + (tid + 256 * i) * 8); \
;     _Pragma("unroll") for (int i = 0; i < 2; ++i) vreg[SET][i] = *(const u32x4*)(Vg + (size_t)kl_ * 64 + (tid + 256 * i) * 8); \
;     __builtin_amdgcn_sched_barrier(0); }
; template <int DQK, bool SB, bool SMAX>
; DI void attn_item(const Params& p, char* smem, int bh, int qb, float Mb) {
;     ...
;   const int blk = (lane >> 4) & 1, tq = (lane & 15) >> 2, tp = lane & 3;
;   const int voff = (4 * h + tq) * VSTR + 16 * blk + 4 * tp;
;   AT_LOAD(0, 0)
;   AT_WRITE(0, 0)
;   AT_LOAD(0, 1)
;   __syncthreads();
;   bool stop = false;
;   for (int it2 = 0; it2 < nt && !stop; it2 += 2) {
; #pragma unroll
;    for (int st2 = 0; st2 < 2; ++st2) {
;     const int it = it2 + st2;
;     const int kb0 = AT_KB(it);
;     const bf16_t* kc = Ks + st2 * KBUF;
;     const bf16_t* vc = Vs + st2 * VBUF;
;     const bool active = kb0 < qw0 + 32;
;     f32x16 st[2];
;     if (active) {
; #pragma unroll
;       for (int kb = 0; kb < 2; ++kb)
; #pragma unroll
;         for (int i = 0; i < 16; ++i) st[kb][i] = SMAX ? negM[i] : 0.f;
; #pragma unroll
;       for (int ks = 0; ks < NKS; ++ks)
; #pragma unroll
;         for (int kb = 0; kb < 2; ++kb) {
;           const bf16x8 a = *(const bf16x8*)(kc + (kb * 32 + r) * KSTR + ks * 16 + h * 8);
;           st[kb] = MFMA32(a, qf[ks], st[kb]);
;         }
;     }
;     __builtin_amdgcn_sched_barrier(0);
;     AT_WRITE(0, st2 ^ 1)
;     AT_LOAD(0, (it + 2 < nt) ? it + 2 : nt - 1)
;     if (active) {
;       const bool diag = (kb0 + 64 > qw0);
;       bf16x8 pk[4];
;       if (!SB) {
;         if (diag) {
; #pragma unroll
;           for (int kb = 0; kb < 2; ++kb)
; #pragma unroll
;             for (int i = 0; i < 16; ++i) { const int key = kb0 + kb * 32 + crow(i, h); if (key > query) st[kb][i] = -__builtin_huge_valf(); }
.Lt15_tail:
	ds_read_b128 v[216:219], v153 offset:13312
	ds_read_b128 v[220:223], v153 offset:19968
	ds_read_b128 v[228:231], v153 offset:13344
	s_min_i32 s2, s14, s4
	s_mul_i32 s3, s2, 0x3000
	s_add_u32 s30, s22, s3
	s_addc_u32 s31, s23, 0
	s_add_u32 s34, s30, 0x1000
	s_addc_u32 s35, s31, 0
	s_add_i32 s3, s14, -1
	s_min_i32 s3, s3, s4
	s_lshl_b32 s3, s3, 13
	s_add_u32 s36, s38, s3
	s_addc_u32 s37, s39, 0
	global_load_dwordx4 v[132:135], v174, s[30:31] offset:-4096
	global_load_dwordx4 v[136:139], v174, s[30:31]
	global_load_dwordx4 v[140:143], v174, s[34:35]
	global_load_dwordx4 v[144:147], v174, s[36:37] offset:-4096
	global_load_dwordx4 v[148:151], v174, s[36:37]
	s_waitcnt vmcnt(9)
	ds_write_b128 v206, v[112:115]
	s_waitcnt vmcnt(8)
	ds_write_b128 v207, v[116:119]
	s_waitcnt vmcnt(7)
	ds_write_b128 v208, v[120:123]
	s_waitcnt vmcnt(6)
	ds_write_b128 v203, v[124:127] offset:35840
	s_waitcnt vmcnt(5)
	ds_write_b128 v203, v[128:131] offset:40448
	s_waitcnt lgkmcnt(7)
	v_mfma_f32_32x32x16_bf16 v[0:15], v[216:219], v[80:83], 0
	ds_read_b128 v[216:219], v153 offset:20000
	s_waitcnt lgkmcnt(7)
	v_mfma_f32_32x32x16_bf16 v[156:171], v[220:223], v[80:83], 0
	ds_read_b128 v[220:223], v153 offset:13376
	s_waitcnt lgkmcnt(7)
	v_mfma_f32_32x32x16_bf16 v[0:15], v[228:231], v[84:87], v[0:15]
	ds_read_b128 v[228:231], v153 offset:20032
	s_waitcnt lgkmcnt(2)
	v_mfma_f32_32x32x16_bf16 v[156:171], v[216:219], v[84:87], v[156:171]
	ds_read_b128 v[216:219], v153 offset:13408
	s_waitcnt lgkmcnt(2)
	v_mfma_f32_32x32x16_bf16 v[0:15], v[220:223], v[88:91], v[0:15]
	ds_read_b128 v[220:223], v153 offset:20064
	s_waitcnt lgkmcnt(2)
	v_mfma_f32_32x32x16_bf16 v[156:171], v[228:231], v[88:91], v[156:171]
	ds_read_b128 v[228:231], v153 offset:13440
	s_waitcnt lgkmcnt(2)
	v_mfma_f32_32x32x16_bf16 v[0:15], v[216:219], v[92:95], v[0:15]
	ds_read_b128 v[216:219], v153 offset:20096
	s_waitcnt lgkmcnt(2)
	v_mfma_f32_32x32x16_bf16 v[156:171], v[220:223], v[92:95], v[156:171]
	ds_read_b128 v[220:223], v153 offset:13472
	s_waitcnt lgkmcnt(2)
	v_mfma_f32_32x32x16_bf16 v[0:15], v[228:231], v[104:107], v[0:15]
	ds_read_b128 v[228:231], v153 offset:20128
	s_waitcnt lgkmcnt(2)
	v_mfma_f32_32x32x16_bf16 v[156:171], v[216:219], v[104:107], v[156:171]
	s_waitcnt lgkmcnt(1)
	v_mfma_f32_32x32x16_bf16 v[0:15], v[220:223], v[108:111], v[0:15]
	s_waitcnt lgkmcnt(0)
	v_mfma_f32_32x32x16_bf16 v[156:171], v[228:231], v[108:111], v[156:171]
	s_lshl_b32 s2, s1, 6
	s_add_i32 s2, s2, 0xffffff80
	s_nop 7
	s_nop 3
	v_add_u32_e32 v227, s2, v197
	v_add_u32_e32 v225, 0, v227
	v_cmp_le_u32_e32 vcc, v225, v176
	s_nop 1
	v_cndmask_b32_e32 v48, v210, v48, vcc
	v_add_u32_e32 v225, 1, v227
	v_cmp_le_u32_e32 vcc, v225, v176
	s_nop 1
	v_cndmask_b32_e32 v49, v210, v49, vcc
	v_add_u32_e32 v225, 2, v227
	v_cmp_le_u32_e32 vcc, v225, v176
	s_nop 1
	v_cndmask_b32_e32 v50, v210, v50, vcc
	v_add_u32_e32 v225, 3, v227
	v_cmp_le_u32_e32 vcc, v225, v176
	s_nop 1
	v_cndmask_b32_e32 v51, v210, v51, vcc
	v_add_u32_e32 v225, 8, v227
	v_cmp_le_u32_e32 vcc, v225, v176
	s_nop 1
	v_cndmask_b32_e32 v52, v210, v52, vcc
	v_add_u32_e32 v225, 9, v227
	v_cmp_le_u32_e32 vcc, v225, v176
	s_nop 1
	v_cndmask_b32_e32 v53, v210, v53, vcc
	v_add_u32_e32 v225, 10, v227
	v_cmp_le_u32_e32 vcc, v225, v176
	s_nop 1
	v_cndmask_b32_e32 v54, v210, v54, vcc
	v_add_u32_e32 v225, 11, v227
	v_cmp_le_u32_e32 vcc, v225, v176
	s_nop 1
	v_cndmask_b32_e32 v55, v210, v55, vcc
	v_add_u32_e32 v225, 16, v227
	v_cmp_le_u32_e32 vcc, v225, v176
	s_nop 1
	v_cndmask_b32_e32 v56, v210, v56, vcc
	v_add_u32_e32 v225, 17, v227
	v_cmp_le_u32_e32 vcc, v225, v176
	s_nop 1
	v_cndmask_b32_e32 v57, v210, v57, vcc
	v_add_u32_e32 v225, 18, v227
	v_cmp_le_u32_e32 vcc, v225, v176
	s_nop 1
	v_cndmask_b32_e32 v58, v210, v58, vcc
	v_add_u32_e32 v225, 19, v227
	v_cmp_le_u32_e32 vcc, v225, v176
	s_nop 1
	v_cndmask_b32_e32 v59, v210, v59, vcc
	v_add_u32_e32 v225, 24, v227
	v_cmp_le_u32_e32 vcc, v225, v176
	s_nop 1
	v_cndmask_b32_e32 v60, v210, v60, vcc
	v_add_u32_e32 v225, 25, v227
	v_cmp_le_u32_e32 vcc, v225, v176
	s_nop 1
	v_cndmask_b32_e32 v61, v210, v61, vcc
	v_add_u32_e32 v225, 26, v227
	v_cmp_le_u32_e32 vcc, v225, v176
	s_nop 1
	v_cndmask_b32_e32 v62, v210, v62, vcc
	v_add_u32_e32 v225, 27, v227
	v_cmp_le_u32_e32 vcc, v225, v176
	s_nop 1
	v_cndmask_b32_e32 v63, v210, v63, vcc
	v_add_u32_e32 v225, 32, v227
	v_cmp_le_u32_e32 vcc, v225, v176
	s_nop 1
	v_cndmask_b32_e32 v64, v210, v64, vcc
	v_add_u32_e32 v225, 33, v227
	v_cmp_le_u32_e32 vcc, v225, v176
	s_nop 1
	v_cndmask_b32_e32 v65, v210, v65, vcc
	v_add_u32_e32 v225, 34, v227
	v_cmp_le_u32_e32 vcc, v225, v176
	s_nop 1
	v_cndmask_b32_e32 v66, v210, v66, vcc
	v_add_u32_e32 v225, 35, v227
	v_cmp_le_u32_e32 vcc, v225, v176
	s_nop 1
	v_cndmask_b32_e32 v67, v210, v67, vcc
	v_add_u32_e32 v225, 40, v227
	v_cmp_le_u32_e32 vcc, v225, v176
	s_nop 1
	v_cndmask_b32_e32 v68, v210, v68, vcc
	v_add_u32_e32 v225, 41, v227
	v_cmp_le_u32_e32 vcc, v225, v176
	s_nop 1
	v_cndmask_b32_e32 v69, v210, v69, vcc
	v_add_u32_e32 v225, 42, v227
	v_cmp_le_u32_e32 vcc, v225, v176
	s_nop 1
	v_cndmask_b32_e32 v70, v210, v70, vcc
	v_add_u32_e32 v225, 43, v227
	v_cmp_le_u32_e32 vcc, v225, v176
	s_nop 1
	v_cndmask_b32_e32 v71, v210, v71, vcc
	v_add_u32_e32 v225, 48, v227
	v_cmp_le_u32_e32 vcc, v225, v176
	s_nop 1
	v_cndmask_b32_e32 v72, v210, v72, vcc
	v_add_u32_e32 v225, 49, v227
	v_cmp_le_u32_e32 vcc, v225, v176
	s_nop 1
	v_cndmask_b32_e32 v73, v210, v73, vcc
	v_add_u32_e32 v225, 50, v227
	v_cmp_le_u32_e32 vcc, v225, v176
	s_nop 1
	v_cndmask_b32_e32 v74, v210, v74, vcc
	v_add_u32_e32 v225, 51, v227
	v_cmp_le_u32_e32 vcc, v225, v176
	s_nop 1
; #define MFMA32(a, b, c) __builtin_amdgcn_mfma_f32_32x32x16_bf16((a), (b), (c), 0, 0, 0)
; DI unsigned pk_bf16(float lo, float hi) { f32x2 v = {lo, hi}; bf2_t b = __builtin_convertvector(v, bf2_t); return __builtin_bit_cast(unsigned, b); }
; DI int crow(int i, int h) { return (i & 3) + 8 * (i >> 2) + 4 * h; }
; DI float fast_exp2(float x) { return __builtin_amdgcn_exp2f(x); }
; template <int DQK, bool SB, bool SMAX>
; DI void attn_item(const Params& p, char* smem, int bh, int qb, float Mb) {
;     ...
;             for (int i = 0; i < 16; ++i) { const int key = kb0 + kb * 32 + crow(i, h); if (key > query) st[kb][i] = -__builtin_huge_valf(); }
;         }
;         if (SMAX) {
;           float ps = 0.f;
; #pragma unroll
;           for (int kb = 0; kb < 2; ++kb)
; #pragma unroll
;             for (int i = 0; i < 16; ++i) { const float pv = fast_exp2(st[kb][i]); st[kb][i] = pv; ps += pv; }
;           lsum += ps;
;     ...
; #pragma unroll
;       for (int kb = 0; kb < 2; ++kb)
; #pragma unroll
;         for (int s = 0; s < 2; ++s) {
;           u32x4 w;
; #pragma unroll
;           for (int e = 0; e < 4; ++e) w[e] = pk_bf16(st[kb][8 * s + 2 * e], st[kb][8 * s + 2 * e + 1]);
;           pk[kb * 2 + s] = __builtin_bit_cast(bf16x8, w);
;         }
; #pragma unroll
;       for (int kk = 0; kk < 4; ++kk)
; #pragma unroll
;         for (int db = 0; db < 2; ++db) {
;           const s16x4 v0 = __builtin_amdgcn_ds_read_tr16_b64_v4i16((lds_s16x4*)(vc + voff + (16 * kk) * VSTR + 32 * db));
;           const s16x4 v1 = __builtin_amdgcn_ds_read_tr16_b64_v4i16((lds_s16x4*)(vc + voff + (16 * kk + 8) * VSTR + 32 * db));
;           const bf16x8 vf = __builtin_shufflevector(v0, v1, 0, 1, 2, 3, 4, 5, 6, 7);
;           O[db] = MFMA32(vf, pk[kk], O[db]);
;         }
	v_cndmask_b32_e32 v75, v210, v75, vcc
	v_add_u32_e32 v225, 56, v227
	v_cmp_le_u32_e32 vcc, v225, v176
	s_nop 1
	v_cndmask_b32_e32 v76, v210, v76, vcc
	v_add_u32_e32 v225, 57, v227
	v_cmp_le_u32_e32 vcc, v225, v176
	s_nop 1
	v_cndmask_b32_e32 v77, v210, v77, vcc
	v_add_u32_e32 v225, 58, v227
	v_cmp_le_u32_e32 vcc, v225, v176
	s_nop 1
	v_cndmask_b32_e32 v78, v210, v78, vcc
	v_add_u32_e32 v225, 59, v227
	v_cmp_le_u32_e32 vcc, v225, v176
	s_nop 1
	v_cndmask_b32_e32 v79, v210, v79, vcc
	ds_read_b64_tr_b16 v[236:237], v154 offset:26624
	ds_read_b64_tr_b16 v[238:239], v154 offset:27776
	ds_read_b64_tr_b16 v[244:245], v154 offset:26688
	ds_read_b64_tr_b16 v[246:247], v154 offset:27840
	ds_read_b64_tr_b16 v[248:249], v154 offset:28928
	ds_read_b64_tr_b16 v[250:251], v154 offset:30080
	v_exp_f32_e32 v48, v48
	v_exp_f32_e32 v49, v49
	v_exp_f32_e32 v50, v50
	v_exp_f32_e32 v51, v51
	v_exp_f32_e32 v52, v52
	v_add_f32_e32 v224, v49, v48
	v_cvt_pk_bf16_f32 v188, v48, v49
	v_exp_f32_e32 v53, v53
	v_add_f32_e32 v224, v50, v224
	v_exp_f32_e32 v54, v54
	v_add_f32_e32 v224, v51, v224
	v_cvt_pk_bf16_f32 v189, v50, v51
	v_exp_f32_e32 v55, v55
	v_add_f32_e32 v224, v52, v224
	v_exp_f32_e32 v56, v56
	v_add_f32_e32 v224, v53, v224
	v_cvt_pk_bf16_f32 v190, v52, v53
	v_exp_f32_e32 v57, v57
	v_add_f32_e32 v224, v54, v224
	v_exp_f32_e32 v58, v58
	v_add_f32_e32 v224, v55, v224
	v_cvt_pk_bf16_f32 v191, v54, v55
	v_exp_f32_e32 v59, v59
	v_add_f32_e32 v224, v56, v224
	v_exp_f32_e32 v60, v60
	v_add_f32_e32 v224, v57, v224
	v_cvt_pk_bf16_f32 v192, v56, v57
	v_exp_f32_e32 v61, v61
	v_add_f32_e32 v224, v58, v224
	v_exp_f32_e32 v62, v62
	v_add_f32_e32 v224, v59, v224
	v_cvt_pk_bf16_f32 v193, v58, v59
	v_exp_f32_e32 v63, v63
	v_add_f32_e32 v224, v60, v224
	v_add_f32_e32 v224, v61, v224
	v_add_f32_e32 v224, v62, v224
	v_add_f32_e32 v224, v63, v224
	v_cvt_pk_bf16_f32 v194, v60, v61
	v_cvt_pk_bf16_f32 v195, v62, v63
	s_nop 1
	s_waitcnt lgkmcnt(4)
	v_mfma_f32_32x32x16_bf16 v[32:47], v[236:239], v[188:191], v[32:47]
	ds_read_b64_tr_b16 v[236:237], v154 offset:28992
	ds_read_b64_tr_b16 v[238:239], v154 offset:30144
	s_waitcnt lgkmcnt(4)
	v_mfma_f32_32x32x16_bf16 v[16:31], v[244:247], v[188:191], v[16:31]
	ds_read_b64_tr_b16 v[244:245], v154 offset:31232
	ds_read_b64_tr_b16 v[246:247], v154 offset:32384
	s_waitcnt lgkmcnt(4)
	v_mfma_f32_32x32x16_bf16 v[32:47], v[248:251], v[192:195], v[32:47]
	ds_read_b64_tr_b16 v[248:249], v154 offset:31296
	ds_read_b64_tr_b16 v[250:251], v154 offset:32448
	s_waitcnt lgkmcnt(4)
	v_mfma_f32_32x32x16_bf16 v[16:31], v[236:239], v[192:195], v[16:31]
	ds_read_b64_tr_b16 v[236:237], v154 offset:33536
	ds_read_b64_tr_b16 v[238:239], v154 offset:34688
	v_exp_f32_e32 v64, v64
	v_exp_f32_e32 v65, v65
	v_exp_f32_e32 v66, v66
	v_exp_f32_e32 v67, v67
	v_add_f32_e32 v224, v64, v224
	v_exp_f32_e32 v68, v68
	v_add_f32_e32 v224, v65, v224
	v_cvt_pk_bf16_f32 v188, v64, v65
	v_exp_f32_e32 v69, v69
	v_add_f32_e32 v224, v66, v224
	v_exp_f32_e32 v70, v70
	v_add_f32_e32 v224, v67, v224
	v_cvt_pk_bf16_f32 v189, v66, v67
	v_exp_f32_e32 v71, v71
	v_add_f32_e32 v224, v68, v224
	v_exp_f32_e32 v72, v72
	v_add_f32_e32 v224, v69, v224
	v_cvt_pk_bf16_f32 v190, v68, v69
	v_exp_f32_e32 v73, v73
	v_add_f32_e32 v224, v70, v224
	v_exp_f32_e32 v74, v74
	v_add_f32_e32 v224, v71, v224
	v_cvt_pk_bf16_f32 v191, v70, v71
	v_exp_f32_e32 v75, v75
	v_add_f32_e32 v224, v72, v224
	v_exp_f32_e32 v76, v76
	v_add_f32_e32 v224, v73, v224
	v_cvt_pk_bf16_f32 v192, v72, v73
	v_exp_f32_e32 v77, v77
	v_add_f32_e32 v224, v74, v224
	v_exp_f32_e32 v78, v78
	v_add_f32_e32 v224, v75, v224
	v_cvt_pk_bf16_f32 v193, v74, v75
	v_exp_f32_e32 v79, v79
	v_add_f32_e32 v224, v76, v224
	v_add_f32_e32 v224, v77, v224
	v_add_f32_e32 v224, v78, v224
	v_add_f32_e32 v224, v79, v224
	v_cvt_pk_bf16_f32 v194, v76, v77
	v_cvt_pk_bf16_f32 v195, v78, v79
	s_nop 1
	s_waitcnt lgkmcnt(4)
	v_mfma_f32_32x32x16_bf16 v[32:47], v[244:247], v[188:191], v[32:47]
	ds_read_b64_tr_b16 v[244:245], v154 offset:33600
	ds_read_b64_tr_b16 v[246:247], v154 offset:34752
	s_waitcnt lgkmcnt(4)
	v_mfma_f32_32x32x16_bf16 v[16:31], v[248:251], v[188:191], v[16:31]
	s_waitcnt lgkmcnt(2)
	v_mfma_f32_32x32x16_bf16 v[32:47], v[236:239], v[192:195], v[32:47]
	s_waitcnt lgkmcnt(0)
	v_mfma_f32_32x32x16_bf16 v[16:31], v[244:247], v[192:195], v[16:31]
	v_add_f32_e32 v152, v152, v224
	s_waitcnt lgkmcnt(0)
	s_barrier
	s_add_i32 s14, s14, 1
	s_lshl_b32 s2, s4, 6
	s_cmp_gt_u32 s2, s20
	s_cbranch_scc1 .Lt15_done
; #define MFMA32(a, b, c) __builtin_amdgcn_mfma_f32_32x32x16_bf16((a), (b), (c), 0, 0, 0)
; DI unsigned pk_bf16(float lo, float hi) { f32x2 v = {lo, hi}; bf2_t b = __builtin_convertvector(v, bf2_t); return __builtin_bit_cast(unsigned, b); }
; DI int crow(int i, int h) { return (i & 3) + 8 * (i >> 2) + 4 * h; }
; DI float fast_exp2(float x) { return __builtin_amdgcn_exp2f(x); }
; template <int DQK, bool SB, bool SMAX>
; DI void attn_item(const Params& p, char* smem, int bh, int qb, float Mb) {
;     ...
;         if (diag) {
; #pragma unroll
;           for (int kb = 0; kb < 2; ++kb)
; #pragma unroll
;             for (int i = 0; i < 16; ++i) { const int key = kb0 + kb * 32 + crow(i, h); if (key > query) st[kb][i] = -__builtin_huge_valf(); }
;         }
;         if (SMAX) {
;           float ps = 0.f;
; #pragma unroll
;           for (int kb = 0; kb < 2; ++kb)
; #pragma unroll
;             for (int i = 0; i < 16; ++i) { const float pv = fast_exp2(st[kb][i]); st[kb][i] = pv; ps += pv; }
;           lsum += ps;
;     ...
; #pragma unroll
;           for (int e = 0; e < 4; ++e) w[e] = pk_bf16(st[kb][8 * s + 2 * e], st[kb][8 * s + 2 * e + 1]);
;           pk[kb * 2 + s] = __builtin_bit_cast(bf16x8, w);
;         }
; #pragma unroll
;       for (int kk = 0; kk < 4; ++kk)
; #pragma unroll
;         for (int db = 0; db < 2; ++db) {
;           const s16x4 v0 = __builtin_amdgcn_ds_read_tr16_b64_v4i16((lds_s16x4*)(vc + voff + (16 * kk) * VSTR + 32 * db));
;           const s16x4 v1 = __builtin_amdgcn_ds_read_tr16_b64_v4i16((lds_s16x4*)(vc + voff + (16 * kk + 8) * VSTR + 32 * db));
;           const bf16x8 vf = __builtin_shufflevector(v0, v1, 0, 1, 2, 3, 4, 5, 6, 7);
;           O[db] = MFMA32(vf, pk[kk], O[db]);
	v_add_u32_e32 v227, s2, v197
	v_add_u32_e32 v225, 0, v227
	v_cmp_le_u32_e32 vcc, v225, v176
	s_nop 1
	v_cndmask_b32_e32 v0, v210, v0, vcc
	v_add_u32_e32 v225, 1, v227
	v_cmp_le_u32_e32 vcc, v225, v176
	s_nop 1
	v_cndmask_b32_e32 v1, v210, v1, vcc
	v_add_u32_e32 v225, 2, v227
	v_cmp_le_u32_e32 vcc, v225, v176
	s_nop 1
	v_cndmask_b32_e32 v2, v210, v2, vcc
	v_add_u32_e32 v225, 3, v227
	v_cmp_le_u32_e32 vcc, v225, v176
	s_nop 1
	v_cndmask_b32_e32 v3, v210, v3, vcc
	v_add_u32_e32 v225, 8, v227
	v_cmp_le_u32_e32 vcc, v225, v176
	s_nop 1
	v_cndmask_b32_e32 v4, v210, v4, vcc
	v_add_u32_e32 v225, 9, v227
	v_cmp_le_u32_e32 vcc, v225, v176
	s_nop 1
	v_cndmask_b32_e32 v5, v210, v5, vcc
	v_add_u32_e32 v225, 10, v227
	v_cmp_le_u32_e32 vcc, v225, v176
	s_nop 1
	v_cndmask_b32_e32 v6, v210, v6, vcc
	v_add_u32_e32 v225, 11, v227
	v_cmp_le_u32_e32 vcc, v225, v176
	s_nop 1
	v_cndmask_b32_e32 v7, v210, v7, vcc
	v_add_u32_e32 v225, 16, v227
	v_cmp_le_u32_e32 vcc, v225, v176
	s_nop 1
	v_cndmask_b32_e32 v8, v210, v8, vcc
	v_add_u32_e32 v225, 17, v227
	v_cmp_le_u32_e32 vcc, v225, v176
	s_nop 1
	v_cndmask_b32_e32 v9, v210, v9, vcc
	v_add_u32_e32 v225, 18, v227
	v_cmp_le_u32_e32 vcc, v225, v176
	s_nop 1
	v_cndmask_b32_e32 v10, v210, v10, vcc
	v_add_u32_e32 v225, 19, v227
	v_cmp_le_u32_e32 vcc, v225, v176
	s_nop 1
	v_cndmask_b32_e32 v11, v210, v11, vcc
	v_add_u32_e32 v225, 24, v227
	v_cmp_le_u32_e32 vcc, v225, v176
	s_nop 1
	v_cndmask_b32_e32 v12, v210, v12, vcc
	v_add_u32_e32 v225, 25, v227
	v_cmp_le_u32_e32 vcc, v225, v176
	s_nop 1
	v_cndmask_b32_e32 v13, v210, v13, vcc
	v_add_u32_e32 v225, 26, v227
	v_cmp_le_u32_e32 vcc, v225, v176
	s_nop 1
	v_cndmask_b32_e32 v14, v210, v14, vcc
	v_add_u32_e32 v225, 27, v227
	v_cmp_le_u32_e32 vcc, v225, v176
	s_nop 1
	v_cndmask_b32_e32 v15, v210, v15, vcc
	v_add_u32_e32 v225, 32, v227
	v_cmp_le_u32_e32 vcc, v225, v176
	s_nop 1
	v_cndmask_b32_e32 v156, v210, v156, vcc
	v_add_u32_e32 v225, 33, v227
	v_cmp_le_u32_e32 vcc, v225, v176
	s_nop 1
	v_cndmask_b32_e32 v157, v210, v157, vcc
	v_add_u32_e32 v225, 34, v227
	v_cmp_le_u32_e32 vcc, v225, v176
	s_nop 1
	v_cndmask_b32_e32 v158, v210, v158, vcc
	v_add_u32_e32 v225, 35, v227
	v_cmp_le_u32_e32 vcc, v225, v176
	s_nop 1
	v_cndmask_b32_e32 v159, v210, v159, vcc
	v_add_u32_e32 v225, 40, v227
	v_cmp_le_u32_e32 vcc, v225, v176
	s_nop 1
	v_cndmask_b32_e32 v160, v210, v160, vcc
	v_add_u32_e32 v225, 41, v227
	v_cmp_le_u32_e32 vcc, v225, v176
	s_nop 1
	v_cndmask_b32_e32 v161, v210, v161, vcc
	v_add_u32_e32 v225, 42, v227
	v_cmp_le_u32_e32 vcc, v225, v176
	s_nop 1
	v_cndmask_b32_e32 v162, v210, v162, vcc
	v_add_u32_e32 v225, 43, v227
	v_cmp_le_u32_e32 vcc, v225, v176
	s_nop 1
	v_cndmask_b32_e32 v163, v210, v163, vcc
	v_add_u32_e32 v225, 48, v227
	v_cmp_le_u32_e32 vcc, v225, v176
	s_nop 1
	v_cndmask_b32_e32 v164, v210, v164, vcc
	v_add_u32_e32 v225, 49, v227
	v_cmp_le_u32_e32 vcc, v225, v176
	s_nop 1
	v_cndmask_b32_e32 v165, v210, v165, vcc
	v_add_u32_e32 v225, 50, v227
	v_cmp_le_u32_e32 vcc, v225, v176
	s_nop 1
	v_cndmask_b32_e32 v166, v210, v166, vcc
	v_add_u32_e32 v225, 51, v227
	v_cmp_le_u32_e32 vcc, v225, v176
	s_nop 1
	v_cndmask_b32_e32 v167, v210, v167, vcc
	v_add_u32_e32 v225, 56, v227
	v_cmp_le_u32_e32 vcc, v225, v176
	s_nop 1
	v_cndmask_b32_e32 v168, v210, v168, vcc
	v_add_u32_e32 v225, 57, v227
	v_cmp_le_u32_e32 vcc, v225, v176
	s_nop 1
	v_cndmask_b32_e32 v169, v210, v169, vcc
	v_add_u32_e32 v225, 58, v227
	v_cmp_le_u32_e32 vcc, v225, v176
	s_nop 1
	v_cndmask_b32_e32 v170, v210, v170, vcc
	v_add_u32_e32 v225, 59, v227
	v_cmp_le_u32_e32 vcc, v225, v176
	s_nop 1
	v_cndmask_b32_e32 v171, v210, v171, vcc
	ds_read_b64_tr_b16 v[236:237], v154 offset:35840
	ds_read_b64_tr_b16 v[238:239], v154 offset:36992
	ds_read_b64_tr_b16 v[244:245], v154 offset:35904
	ds_read_b64_tr_b16 v[246:247], v154 offset:37056
	ds_read_b64_tr_b16 v[248:249], v154 offset:38144
	ds_read_b64_tr_b16 v[250:251], v154 offset:39296
	v_exp_f32_e32 v0, v0
	v_exp_f32_e32 v1, v1
	v_exp_f32_e32 v2, v2
	v_exp_f32_e32 v3, v3
	v_exp_f32_e32 v4, v4
	v_add_f32_e32 v224, v1, v0
	v_cvt_pk_bf16_f32 v188, v0, v1
	v_exp_f32_e32 v5, v5
	v_add_f32_e32 v224, v2, v224
	v_exp_f32_e32 v6, v6
	v_add_f32_e32 v224, v3, v224
	v_cvt_pk_bf16_f32 v189, v2, v3
	v_exp_f32_e32 v7, v7
	v_add_f32_e32 v224, v4, v224
	v_exp_f32_e32 v8, v8
	v_add_f32_e32 v224, v5, v224
	v_cvt_pk_bf16_f32 v190, v4, v5
	v_exp_f32_e32 v9, v9
	v_add_f32_e32 v224, v6, v224
	v_exp_f32_e32 v10, v10
	v_add_f32_e32 v224, v7, v224
	v_cvt_pk_bf16_f32 v191, v6, v7
	v_exp_f32_e32 v11, v11
	v_add_f32_e32 v224, v8, v224
	v_exp_f32_e32 v12, v12
	v_add_f32_e32 v224, v9, v224
	v_cvt_pk_bf16_f32 v192, v8, v9
	v_exp_f32_e32 v13, v13
	v_add_f32_e32 v224, v10, v224
	v_exp_f32_e32 v14, v14
	v_add_f32_e32 v224, v11, v224
	v_cvt_pk_bf16_f32 v193, v10, v11
	v_exp_f32_e32 v15, v15
	v_add_f32_e32 v224, v12, v224
	v_add_f32_e32 v224, v13, v224
	v_add_f32_e32 v224, v14, v224
	v_add_f32_e32 v224, v15, v224
	v_cvt_pk_bf16_f32 v194, v12, v13
	v_cvt_pk_bf16_f32 v195, v14, v15
	s_nop 1
	s_waitcnt lgkmcnt(4)
; #define MFMA32(a, b, c) __builtin_amdgcn_mfma_f32_32x32x16_bf16((a), (b), (c), 0, 0, 0)
; DI unsigned pk_bf16(float lo, float hi) { f32x2 v = {lo, hi}; bf2_t b = __builtin_convertvector(v, bf2_t); return __builtin_bit_cast(unsigned, b); }
; DI float fast_exp2(float x) { return __builtin_amdgcn_exp2f(x); }
; template <int DQK, bool SB, bool SMAX>
; DI void attn_item(const Params& p, char* smem, int bh, int qb, float Mb) {
;     ...
;         if (SMAX) {
;           float ps = 0.f;
; #pragma unroll
;           for (int kb = 0; kb < 2; ++kb)
; #pragma unroll
;             for (int i = 0; i < 16; ++i) { const float pv = fast_exp2(st[kb][i]); st[kb][i] = pv; ps += pv; }
;           lsum += ps;
;     ...
; #pragma unroll
;           for (int e = 0; e < 4; ++e) w[e] = pk_bf16(st[kb][8 * s + 2 * e], st[kb][8 * s + 2 * e + 1]);
;           pk[kb * 2 + s] = __builtin_bit_cast(bf16x8, w);
;         }
; #pragma unroll
;       for (int kk = 0; kk < 4; ++kk)
; #pragma unroll
;         for (int db = 0; db < 2; ++db) {
;           const s16x4 v0 = __builtin_amdgcn_ds_read_tr16_b64_v4i16((lds_s16x4*)(vc + voff + (16 * kk) * VSTR + 32 * db));
;           const s16x4 v1 = __builtin_amdgcn_ds_read_tr16_b64_v4i16((lds_s16x4*)(vc + voff + (16 * kk + 8) * VSTR + 32 * db));
;           const bf16x8 vf = __builtin_shufflevector(v0, v1, 0, 1, 2, 3, 4, 5, 6, 7);
;           O[db] = MFMA32(vf, pk[kk], O[db]);
	v_mfma_f32_32x32x16_bf16 v[32:47], v[236:239], v[188:191], v[32:47]
	ds_read_b64_tr_b16 v[236:237], v154 offset:38208
	ds_read_b64_tr_b16 v[238:239], v154 offset:39360
	s_waitcnt lgkmcnt(4)
	v_mfma_f32_32x32x16_bf16 v[16:31], v[244:247], v[188:191], v[16:31]
	ds_read_b64_tr_b16 v[244:245], v154 offset:40448
	ds_read_b64_tr_b16 v[246:247], v154 offset:41600
	s_waitcnt lgkmcnt(4)
	v_mfma_f32_32x32x16_bf16 v[32:47], v[248:251], v[192:195], v[32:47]
	ds_read_b64_tr_b16 v[248:249], v154 offset:40512
	ds_read_b64_tr_b16 v[250:251], v154 offset:41664
	s_waitcnt lgkmcnt(4)
	v_mfma_f32_32x32x16_bf16 v[16:31], v[236:239], v[192:195], v[16:31]
	ds_read_b64_tr_b16 v[236:237], v154 offset:42752
	ds_read_b64_tr_b16 v[238:239], v154 offset:43904
	v_exp_f32_e32 v156, v156
	v_exp_f32_e32 v157, v157
	v_exp_f32_e32 v158, v158
	v_exp_f32_e32 v159, v159
	v_add_f32_e32 v224, v156, v224
	v_exp_f32_e32 v160, v160
	v_add_f32_e32 v224, v157, v224
	v_cvt_pk_bf16_f32 v188, v156, v157
	v_exp_f32_e32 v161, v161
	v_add_f32_e32 v224, v158, v224
	v_exp_f32_e32 v162, v162
	v_add_f32_e32 v224, v159, v224
	v_cvt_pk_bf16_f32 v189, v158, v159
	v_exp_f32_e32 v163, v163
	v_add_f32_e32 v224, v160, v224
	v_exp_f32_e32 v164, v164
	v_add_f32_e32 v224, v161, v224
	v_cvt_pk_bf16_f32 v190, v160, v161
	v_exp_f32_e32 v165, v165
	v_add_f32_e32 v224, v162, v224
	v_exp_f32_e32 v166, v166
	v_add_f32_e32 v224, v163, v224
	v_cvt_pk_bf16_f32 v191, v162, v163
	v_exp_f32_e32 v167, v167
	v_add_f32_e32 v224, v164, v224
	v_exp_f32_e32 v168, v168
	v_add_f32_e32 v224, v165, v224
	v_cvt_pk_bf16_f32 v192, v164, v165
	v_exp_f32_e32 v169, v169
	v_add_f32_e32 v224, v166, v224
	v_exp_f32_e32 v170, v170
	v_add_f32_e32 v224, v167, v224
	v_cvt_pk_bf16_f32 v193, v166, v167
	v_exp_f32_e32 v171, v171
	v_add_f32_e32 v224, v168, v224
	v_add_f32_e32 v224, v169, v224
	v_add_f32_e32 v224, v170, v224
	v_add_f32_e32 v224, v171, v224
	v_cvt_pk_bf16_f32 v194, v168, v169
	v_cvt_pk_bf16_f32 v195, v170, v171
	s_nop 1
	s_waitcnt lgkmcnt(4)
	v_mfma_f32_32x32x16_bf16 v[32:47], v[244:247], v[188:191], v[32:47]
	ds_read_b64_tr_b16 v[244:245], v154 offset:42816
	ds_read_b64_tr_b16 v[246:247], v154 offset:43968
	s_waitcnt lgkmcnt(4)
	v_mfma_f32_32x32x16_bf16 v[16:31], v[248:251], v[188:191], v[16:31]
	s_waitcnt lgkmcnt(2)
	v_mfma_f32_32x32x16_bf16 v[32:47], v[236:239], v[192:195], v[32:47]
	s_waitcnt lgkmcnt(0)
	v_mfma_f32_32x32x16_bf16 v[16:31], v[244:247], v[192:195], v[16:31]
	v_add_f32_e32 v152, v152, v224
	s_waitcnt lgkmcnt(0)
